# in-proj/Q/K epilogues rewritten with 16-byte stores (permlane16 exchange), mlaprep row prefetch, plus earlier de-serialized epilogues and scans
# speedup vs baseline: 1.0433x; 1.0162x over previous
; __device__ __forceinline__ unsigned pk2(float lo, float hi) { const f2_t v = {lo, hi}; return __builtin_bit_cast(unsigned, __builtin_convertvector(v, bf2_t)); }
; #define EPI_LOOP for (int ai = 0; ai < 2; ++ai) for (int bj = 0; bj < 2; ++bj) for (int m = 0; m < 4; ++m) for (int n = 0; n < 2; ++n)
;   __device__ __forceinline__ void operator()(const f32x4 (&acc)[2][2][4][2], int pm, int pn, int wr, int wc, int fr, int fq, bf16_t* shm, int tid) const {
; #pragma unroll
;     EPI_LOOP { EPI_RC
;       const float s = rstd[2 * row] * (0.10206207261596577f * 1.4426950408889634f);
;       u32x2 w; w.x = pk2(v[0] * s, v[1] * s); w.y = pk2(v[2] * s, v[3] * s); *(u32x2*)(Q + (long)row * 768 + col) = w; }
;   }
.LBB0_682:
	v_add_u32_e32 v144, s23, v248
	v_lshlrev_b32_e32 v130, 1, v144
	v_readlane_b32 s40, v253, 7
	v_ashrrev_i32_e32 v131, 31, v130
	v_readlane_b32 s52, v253, 19
	v_readlane_b32 s53, v253, 20
	s_nop 15
	s_nop 15
	v_mbcnt_lo_u32_b32 v0, -1, 0
	v_mbcnt_hi_u32_b32 v0, -1, v0
	v_readlane_b32 s41, v253, 8
	v_or_b32_e32 v132, s12, v249
	v_lshl_add_u64 v[140:141], v[130:131], 2, s[52:53]
	v_mov_b64_e32 v[130:131], s[40:41]
	s_movk_i32 s12, 0x600
	v_ashrrev_i32_e32 v133, 31, v132
	v_mad_i64_i32 v[142:143], s[10:11], v144, s12, v[130:131]
	v_lshlrev_b64 v[132:133], 1, v[132:133]
	v_lshl_add_u64 v[142:143], v[142:143], 0, v[132:133]
	s_andn2_b64 vcc, exec, s[8:9]
	global_load_dword v150, v[140:141], off
	global_load_dword v151, v[140:141], off offset:128
	global_load_dword v152, v[140:141], off offset:256
	global_load_dword v153, v[140:141], off offset:384
	global_load_dword v154, v[140:141], off offset:1024
	global_load_dword v155, v[140:141], off offset:1152
	global_load_dword v156, v[140:141], off offset:1280
	global_load_dword v157, v[140:141], off offset:1408
	s_mov_b32 s43, 0
	s_mov_b32 s42, 0x6000
	v_lshl_add_u64 v[160:161], v[142:143], 0, s[42:43]
	s_mov_b32 s42, 0xc000
	v_lshl_add_u64 v[162:163], v[142:143], 0, s[42:43]
	s_mov_b32 s42, 0x12000
	v_lshl_add_u64 v[164:165], v[142:143], 0, s[42:43]
	s_mov_b32 s42, 0x30000
	v_lshl_add_u64 v[166:167], v[142:143], 0, s[42:43]
	s_mov_b32 s42, 0x36000
	v_lshl_add_u64 v[168:169], v[142:143], 0, s[42:43]
	s_mov_b32 s42, 0x3c000
	v_lshl_add_u64 v[170:171], v[142:143], 0, s[42:43]
	s_mov_b32 s42, 0x42000
	v_lshl_add_u64 v[172:173], v[142:143], 0, s[42:43]
	s_waitcnt vmcnt(0)
	v_mul_f32_e32 v150, 0x3e16c740, v150
	v_mul_f32_e32 v151, 0x3e16c740, v151
	v_mul_f32_e32 v152, 0x3e16c740, v152
	v_mul_f32_e32 v153, 0x3e16c740, v153
	v_mul_f32_e32 v154, 0x3e16c740, v154
	v_mul_f32_e32 v155, 0x3e16c740, v155
	v_mul_f32_e32 v156, 0x3e16c740, v156
	v_mul_f32_e32 v157, 0x3e16c740, v157
	v_and_b32_e32 v196, 4, v249
	v_mul_u32_u24_e32 v196, 6, v196
	v_mov_b32_e32 v197, v1
	v_lshl_add_u64 v[142:143], v[142:143], 0, v[196:197]
	v_lshl_add_u64 v[160:161], v[160:161], 0, v[196:197]
	v_lshl_add_u64 v[162:163], v[162:163], 0, v[196:197]
	v_lshl_add_u64 v[164:165], v[164:165], 0, v[196:197]
	v_lshl_add_u64 v[166:167], v[166:167], 0, v[196:197]
	v_lshl_add_u64 v[168:169], v[168:169], 0, v[196:197]
	v_lshl_add_u64 v[170:171], v[170:171], 0, v[196:197]
	v_lshl_add_u64 v[172:173], v[172:173], 0, v[196:197]
	v_pk_mul_f32 v[126:127], v[126:127], v[150:151] op_sel_hi:[1,0]
	v_pk_mul_f32 v[128:129], v[128:129], v[150:151] op_sel_hi:[1,0]
	v_pk_mul_f32 v[122:123], v[122:123], v[150:151] op_sel_hi:[1,0]
	v_pk_mul_f32 v[124:125], v[124:125], v[150:151] op_sel_hi:[1,0]
	v_pk_mul_f32 v[118:119], v[118:119], v[150:151] op_sel:[0,1]
	v_pk_mul_f32 v[120:121], v[120:121], v[150:151] op_sel:[0,1]
	v_pk_mul_f32 v[114:115], v[114:115], v[150:151] op_sel:[0,1]
	v_pk_mul_f32 v[116:117], v[116:117], v[150:151] op_sel:[0,1]
	v_pk_mul_f32 v[110:111], v[110:111], v[152:153] op_sel_hi:[1,0]
	v_pk_mul_f32 v[112:113], v[112:113], v[152:153] op_sel_hi:[1,0]
	v_pk_mul_f32 v[106:107], v[106:107], v[152:153] op_sel_hi:[1,0]
	v_pk_mul_f32 v[108:109], v[108:109], v[152:153] op_sel_hi:[1,0]
	v_pk_mul_f32 v[102:103], v[102:103], v[152:153] op_sel:[0,1]
	v_pk_mul_f32 v[104:105], v[104:105], v[152:153] op_sel:[0,1]
	v_pk_mul_f32 v[98:99], v[98:99], v[152:153] op_sel:[0,1]
	v_pk_mul_f32 v[100:101], v[100:101], v[152:153] op_sel:[0,1]
	v_pk_mul_f32 v[94:95], v[94:95], v[150:151] op_sel_hi:[1,0]
	v_pk_mul_f32 v[96:97], v[96:97], v[150:151] op_sel_hi:[1,0]
	v_pk_mul_f32 v[90:91], v[90:91], v[150:151] op_sel_hi:[1,0]
	v_pk_mul_f32 v[92:93], v[92:93], v[150:151] op_sel_hi:[1,0]
	v_pk_mul_f32 v[86:87], v[86:87], v[150:151] op_sel:[0,1]
	v_pk_mul_f32 v[88:89], v[88:89], v[150:151] op_sel:[0,1]
	v_pk_mul_f32 v[82:83], v[82:83], v[150:151] op_sel:[0,1]
	v_pk_mul_f32 v[84:85], v[84:85], v[150:151] op_sel:[0,1]
	v_pk_mul_f32 v[78:79], v[78:79], v[152:153] op_sel_hi:[1,0]
	v_pk_mul_f32 v[80:81], v[80:81], v[152:153] op_sel_hi:[1,0]
	v_pk_mul_f32 v[74:75], v[74:75], v[152:153] op_sel_hi:[1,0]
	v_pk_mul_f32 v[76:77], v[76:77], v[152:153] op_sel_hi:[1,0]
	v_pk_mul_f32 v[70:71], v[70:71], v[152:153] op_sel:[0,1]
	v_pk_mul_f32 v[72:73], v[72:73], v[152:153] op_sel:[0,1]
	v_pk_mul_f32 v[66:67], v[66:67], v[152:153] op_sel:[0,1]
	v_pk_mul_f32 v[68:69], v[68:69], v[152:153] op_sel:[0,1]
	v_pk_mul_f32 v[62:63], v[62:63], v[154:155] op_sel_hi:[1,0]
	v_pk_mul_f32 v[64:65], v[64:65], v[154:155] op_sel_hi:[1,0]
	v_pk_mul_f32 v[58:59], v[58:59], v[154:155] op_sel_hi:[1,0]
	v_pk_mul_f32 v[60:61], v[60:61], v[154:155] op_sel_hi:[1,0]
	v_pk_mul_f32 v[54:55], v[54:55], v[154:155] op_sel:[0,1]
	v_pk_mul_f32 v[56:57], v[56:57], v[154:155] op_sel:[0,1]
	v_pk_mul_f32 v[50:51], v[50:51], v[154:155] op_sel:[0,1]
	v_pk_mul_f32 v[52:53], v[52:53], v[154:155] op_sel:[0,1]
	v_pk_mul_f32 v[46:47], v[46:47], v[156:157] op_sel_hi:[1,0]
	v_pk_mul_f32 v[48:49], v[48:49], v[156:157] op_sel_hi:[1,0]
	v_pk_mul_f32 v[42:43], v[42:43], v[156:157] op_sel_hi:[1,0]
	v_pk_mul_f32 v[44:45], v[44:45], v[156:157] op_sel_hi:[1,0]
	v_pk_mul_f32 v[38:39], v[38:39], v[156:157] op_sel:[0,1]
	v_pk_mul_f32 v[40:41], v[40:41], v[156:157] op_sel:[0,1]
; __device__ __forceinline__ unsigned pk2(float lo, float hi) { const f2_t v = {lo, hi}; return __builtin_bit_cast(unsigned, __builtin_convertvector(v, bf2_t)); }
; #define EPI_LOOP for (int ai = 0; ai < 2; ++ai) for (int bj = 0; bj < 2; ++bj) for (int m = 0; m < 4; ++m) for (int n = 0; n < 2; ++n)
;   __device__ __forceinline__ void operator()(const f32x4 (&acc)[2][2][4][2], int pm, int pn, int wr, int wc, int fr, int fq, bf16_t* shm, int tid) const {
; #pragma unroll
;     EPI_LOOP { EPI_RC
;       const float s = rstd[2 * row] * (0.10206207261596577f * 1.4426950408889634f);
;       u32x2 w; w.x = pk2(v[0] * s, v[1] * s); w.y = pk2(v[2] * s, v[3] * s); *(u32x2*)(Q + (long)row * 768 + col) = w; }
;   }
	v_pk_mul_f32 v[34:35], v[34:35], v[156:157] op_sel:[0,1]
	v_pk_mul_f32 v[36:37], v[36:37], v[156:157] op_sel:[0,1]
	v_pk_mul_f32 v[30:31], v[30:31], v[154:155] op_sel_hi:[1,0]
	v_pk_mul_f32 v[32:33], v[32:33], v[154:155] op_sel_hi:[1,0]
	v_pk_mul_f32 v[26:27], v[26:27], v[154:155] op_sel_hi:[1,0]
	v_pk_mul_f32 v[28:29], v[28:29], v[154:155] op_sel_hi:[1,0]
	v_pk_mul_f32 v[22:23], v[22:23], v[154:155] op_sel:[0,1]
	v_pk_mul_f32 v[24:25], v[24:25], v[154:155] op_sel:[0,1]
	v_pk_mul_f32 v[18:19], v[18:19], v[154:155] op_sel:[0,1]
	v_pk_mul_f32 v[20:21], v[20:21], v[154:155] op_sel:[0,1]
	v_pk_mul_f32 v[14:15], v[14:15], v[156:157] op_sel_hi:[1,0]
	v_pk_mul_f32 v[16:17], v[16:17], v[156:157] op_sel_hi:[1,0]
	v_pk_mul_f32 v[10:11], v[10:11], v[156:157] op_sel_hi:[1,0]
	v_pk_mul_f32 v[12:13], v[12:13], v[156:157] op_sel_hi:[1,0]
	v_pk_mul_f32 v[6:7], v[6:7], v[156:157] op_sel:[0,1]
	v_pk_mul_f32 v[8:9], v[8:9], v[156:157] op_sel:[0,1]
	v_pk_mul_f32 v[2:3], v[2:3], v[156:157] op_sel:[0,1]
	v_pk_mul_f32 v[4:5], v[4:5], v[156:157] op_sel:[0,1]
	s_nop 0
	v_cvt_pk_bf16_f32 v126, v126, v127
	v_cvt_pk_bf16_f32 v127, v128, v129
	v_cvt_pk_bf16_f32 v128, v122, v123
	v_cvt_pk_bf16_f32 v129, v124, v125
	v_cvt_pk_bf16_f32 v118, v118, v119
	v_cvt_pk_bf16_f32 v119, v120, v121
	v_cvt_pk_bf16_f32 v120, v114, v115
	v_cvt_pk_bf16_f32 v121, v116, v117
	v_cvt_pk_bf16_f32 v110, v110, v111
	v_cvt_pk_bf16_f32 v111, v112, v113
	v_cvt_pk_bf16_f32 v112, v106, v107
	v_cvt_pk_bf16_f32 v113, v108, v109
	v_cvt_pk_bf16_f32 v102, v102, v103
	v_cvt_pk_bf16_f32 v103, v104, v105
	v_cvt_pk_bf16_f32 v104, v98, v99
	v_cvt_pk_bf16_f32 v105, v100, v101
	v_cvt_pk_bf16_f32 v94, v94, v95
	v_cvt_pk_bf16_f32 v95, v96, v97
	v_cvt_pk_bf16_f32 v96, v90, v91
	v_cvt_pk_bf16_f32 v97, v92, v93
	v_cvt_pk_bf16_f32 v86, v86, v87
	v_cvt_pk_bf16_f32 v87, v88, v89
	v_cvt_pk_bf16_f32 v88, v82, v83
	v_cvt_pk_bf16_f32 v89, v84, v85
	v_cvt_pk_bf16_f32 v78, v78, v79
	v_cvt_pk_bf16_f32 v79, v80, v81
	v_cvt_pk_bf16_f32 v80, v74, v75
	v_cvt_pk_bf16_f32 v81, v76, v77
	v_cvt_pk_bf16_f32 v70, v70, v71
	v_cvt_pk_bf16_f32 v71, v72, v73
	v_cvt_pk_bf16_f32 v72, v66, v67
	v_cvt_pk_bf16_f32 v73, v68, v69
	v_cvt_pk_bf16_f32 v62, v62, v63
	v_cvt_pk_bf16_f32 v63, v64, v65
	v_cvt_pk_bf16_f32 v64, v58, v59
	v_cvt_pk_bf16_f32 v65, v60, v61
	v_cvt_pk_bf16_f32 v54, v54, v55
	v_cvt_pk_bf16_f32 v55, v56, v57
	v_cvt_pk_bf16_f32 v56, v50, v51
	v_cvt_pk_bf16_f32 v57, v52, v53
	v_cvt_pk_bf16_f32 v46, v46, v47
	v_cvt_pk_bf16_f32 v47, v48, v49
	v_cvt_pk_bf16_f32 v48, v42, v43
	v_cvt_pk_bf16_f32 v49, v44, v45
	v_cvt_pk_bf16_f32 v38, v38, v39
	v_cvt_pk_bf16_f32 v39, v40, v41
	v_cvt_pk_bf16_f32 v40, v34, v35
	v_cvt_pk_bf16_f32 v41, v36, v37
	v_cvt_pk_bf16_f32 v30, v30, v31
	v_cvt_pk_bf16_f32 v31, v32, v33
	v_cvt_pk_bf16_f32 v32, v26, v27
	v_cvt_pk_bf16_f32 v33, v28, v29
	v_cvt_pk_bf16_f32 v22, v22, v23
	v_cvt_pk_bf16_f32 v23, v24, v25
	v_cvt_pk_bf16_f32 v24, v18, v19
	v_cvt_pk_bf16_f32 v25, v20, v21
	v_cvt_pk_bf16_f32 v14, v14, v15
	v_cvt_pk_bf16_f32 v15, v16, v17
	v_cvt_pk_bf16_f32 v16, v10, v11
	v_cvt_pk_bf16_f32 v17, v12, v13
	v_cvt_pk_bf16_f32 v6, v6, v7
	v_cvt_pk_bf16_f32 v7, v8, v9
	v_cvt_pk_bf16_f32 v8, v2, v3
	v_cvt_pk_bf16_f32 v9, v4, v5
	s_nop 1
	v_permlane16_swap_b32_e32 v126, v128
	v_permlane16_swap_b32_e32 v127, v129
	v_permlane16_swap_b32_e32 v118, v120
	v_permlane16_swap_b32_e32 v119, v121
	v_permlane16_swap_b32_e32 v110, v112
	v_permlane16_swap_b32_e32 v111, v113
	v_permlane16_swap_b32_e32 v102, v104
	v_permlane16_swap_b32_e32 v103, v105
	v_permlane16_swap_b32_e32 v94, v96
	v_permlane16_swap_b32_e32 v95, v97
	v_permlane16_swap_b32_e32 v86, v88
	v_permlane16_swap_b32_e32 v87, v89
	v_permlane16_swap_b32_e32 v78, v80
	v_permlane16_swap_b32_e32 v79, v81
	v_permlane16_swap_b32_e32 v70, v72
	v_permlane16_swap_b32_e32 v71, v73
	v_permlane16_swap_b32_e32 v62, v64
	v_permlane16_swap_b32_e32 v63, v65
	v_permlane16_swap_b32_e32 v54, v56
	v_permlane16_swap_b32_e32 v55, v57
	v_permlane16_swap_b32_e32 v46, v48
	v_permlane16_swap_b32_e32 v47, v49
	v_permlane16_swap_b32_e32 v38, v40
	v_permlane16_swap_b32_e32 v39, v41
	v_permlane16_swap_b32_e32 v30, v32
	v_permlane16_swap_b32_e32 v31, v33
	v_permlane16_swap_b32_e32 v22, v24
	v_permlane16_swap_b32_e32 v23, v25
	v_permlane16_swap_b32_e32 v14, v16
	v_permlane16_swap_b32_e32 v15, v17
	v_permlane16_swap_b32_e32 v6, v8
	v_permlane16_swap_b32_e32 v7, v9
	global_store_dwordx4 v[142:143], v[126:129], off
	global_store_dwordx4 v[160:161], v[118:121], off
	global_store_dwordx4 v[162:163], v[110:113], off
	global_store_dwordx4 v[164:165], v[102:105], off
	global_store_dwordx4 v[142:143], v[94:97], off offset:256
	global_store_dwordx4 v[160:161], v[86:89], off offset:256
	global_store_dwordx4 v[162:163], v[78:81], off offset:256
	global_store_dwordx4 v[164:165], v[70:73], off offset:256
	global_store_dwordx4 v[166:167], v[62:65], off
	global_store_dwordx4 v[168:169], v[54:57], off
	global_store_dwordx4 v[170:171], v[46:49], off
	global_store_dwordx4 v[172:173], v[38:41], off
	global_store_dwordx4 v[166:167], v[30:33], off offset:256
	global_store_dwordx4 v[168:169], v[22:25], off offset:256
	global_store_dwordx4 v[170:171], v[14:17], off offset:256
	global_store_dwordx4 v[172:173], v[6:9], off offset:256
	s_waitcnt vmcnt(0)
	s_cbranch_vccz .LBB0_691

; __device__ __forceinline__ unsigned pk2(float lo, float hi) { const f2_t v = {lo, hi}; return __builtin_bit_cast(unsigned, __builtin_convertvector(v, bf2_t)); }
; #define EPI_LOOP for (int ai = 0; ai < 2; ++ai) for (int bj = 0; bj < 2; ++bj) for (int m = 0; m < 4; ++m) for (int n = 0; n < 2; ++n)
;   __device__ __forceinline__ void operator()(const f32x4 (&acc)[2][2][4][2], int pm, int pn, int wr_, int wc_, int fr_, int fq_, bf16_t* shm, int tid) const {
;     const int wr = tid >> 8, wc = (tid >> 6) & 3, fr = tid & 15, fq = (tid >> 4) & 3;
; #pragma unroll
;     EPI_LOOP { EPI_RC
;       const float s = rstd[2 * row + 1];
;       int b, key; if (row < NLAT) { b = row >> 11; key = row & 2047; } else { b = (row - NLAT) >> 8; key = 2048 + ((row - NLAT) & 255); }
;       const int h = col >> 6, d = col & 63;
;       u32x2 w; w.x = pk2(v[0] * s, v[1] * s); w.y = pk2(v[2] * s, v[3] * s);
;       *(u32x2*)(Kn + (((long)(b * 8 + h) * 2304 + key) << 6) + d) = w; }
;   }
.LBB0_693:
	v_readlane_b32 s10, v250, 0
	s_nop 15
	s_nop 15
	v_mbcnt_lo_u32_b32 v0, -1, 0
	v_mbcnt_hi_u32_b32 v0, -1, v0
	v_readlane_b32 s16, v253, 7
	v_and_b32_e32 v146, 15, v0
	v_add_u32_e32 v139, s10, v0
	v_ashrrev_i32_e32 v130, 2, v139
	v_and_b32_e32 v130, 0xffffffc0, v130
	v_add_u32_e32 v147, s14, v130
	v_or_b32_e32 v148, v147, v146
	v_lshlrev_b32_e32 v130, 1, v148
	v_ashrrev_i32_e32 v131, 31, v130
	v_readlane_b32 s28, v253, 19
	v_readlane_b32 s29, v253, 20
	v_lshrrev_b32_e32 v0, 2, v0
	v_and_b32_e32 v0, 12, v0
	v_lshl_add_u64 v[132:133], v[130:131], 2, s[28:29]
	v_lshrrev_b32_e32 v130, 1, v139
	s_lshl_b32 s10, s13, 8
	v_and_or_b32 v0, v130, 32, v0
	v_and_or_b32 v139, v130, 64, s10
	v_lshlrev_b32_e32 v130, 1, v0
	v_add_u32_e32 v0, 0xffff0000, v147
	s_movk_i32 s15, 0xcf
	v_lshrrev_b32_e32 v145, 6, v139
	v_ashrrev_i32_e32 v139, 11, v147
	v_bitop3_b32 v140, v147, s15, v146 bitop3:0xc8
	v_lshrrev_b32_e32 v149, 8, v0
	v_cmp_gt_i32_e32 vcc, s63, v148
	s_movk_i32 s16, 0x7cf
	v_or_b32_e32 v0, 0x800, v140
	v_cndmask_b32_e32 v140, v149, v139, vcc
	v_bitop3_b32 v141, v147, s16, v146 bitop3:0xc8
	v_lshlrev_b32_e32 v150, 3, v140
	v_cndmask_b32_e32 v0, v0, v141, vcc
	v_add_u32_e32 v140, v150, v145
	s_movk_i32 s13, 0x900
	v_mad_i64_i32 v[140:141], s[10:11], v140, s13, v[0:1]
	v_readlane_b32 s18, v253, 9
	v_readlane_b32 s19, v253, 10
	v_lshlrev_b64 v[140:141], 7, v[140:141]
	v_mov_b32_e32 v131, v1
	v_lshl_add_u64 v[140:141], s[18:19], 0, v[140:141]
	v_lshl_add_u64 v[140:141], v[140:141], 0, v[130:131]
	global_load_dword v150, v[132:133], off offset:4
	global_load_dword v151, v[132:133], off offset:132
	global_load_dword v152, v[132:133], off offset:260
	global_load_dword v153, v[132:133], off offset:388
	global_load_dword v154, v[132:133], off offset:1028
	global_load_dword v155, v[132:133], off offset:1156
	global_load_dword v156, v[132:133], off offset:1284
	global_load_dword v157, v[132:133], off offset:1412
	s_mov_b32 s45, 0
	s_mov_b32 s44, 0x800
	v_lshl_add_u64 v[160:161], v[140:141], 0, s[44:45]
	s_mov_b32 s44, 0x1000
	v_lshl_add_u64 v[162:163], v[140:141], 0, s[44:45]
	s_mov_b32 s44, 0x1800
	v_lshl_add_u64 v[164:165], v[140:141], 0, s[44:45]
	s_mov_b32 s44, 0x4000
	v_lshl_add_u64 v[166:167], v[140:141], 0, s[44:45]
	s_mov_b32 s44, 0x4800
	v_lshl_add_u64 v[168:169], v[140:141], 0, s[44:45]
	s_mov_b32 s44, 0x5000
	v_lshl_add_u64 v[170:171], v[140:141], 0, s[44:45]
	s_mov_b32 s44, 0x5800
	v_lshl_add_u64 v[172:173], v[140:141], 0, s[44:45]
	s_mov_b32 s44, 0x90000
	v_lshl_add_u64 v[174:175], v[140:141], 0, s[44:45]
	v_lshl_add_u64 v[176:177], v[160:161], 0, s[44:45]
	v_lshl_add_u64 v[178:179], v[162:163], 0, s[44:45]
	v_lshl_add_u64 v[180:181], v[164:165], 0, s[44:45]
	v_lshl_add_u64 v[182:183], v[166:167], 0, s[44:45]
	v_lshl_add_u64 v[184:185], v[168:169], 0, s[44:45]
	v_lshl_add_u64 v[186:187], v[170:171], 0, s[44:45]
	v_lshl_add_u64 v[188:189], v[172:173], 0, s[44:45]
	s_waitcnt vmcnt(0)
	v_and_b32_e32 v196, 8, v130
	v_mul_u32_u24_e32 v196, 3, v196
	v_mov_b32_e32 v197, v1
	v_lshl_add_u64 v[140:141], v[140:141], 0, v[196:197]
	v_lshl_add_u64 v[160:161], v[160:161], 0, v[196:197]
	v_lshl_add_u64 v[162:163], v[162:163], 0, v[196:197]
	v_lshl_add_u64 v[164:165], v[164:165], 0, v[196:197]
	v_lshl_add_u64 v[166:167], v[166:167], 0, v[196:197]
	v_lshl_add_u64 v[168:169], v[168:169], 0, v[196:197]
	v_lshl_add_u64 v[170:171], v[170:171], 0, v[196:197]
	v_lshl_add_u64 v[172:173], v[172:173], 0, v[196:197]
	v_lshl_add_u64 v[174:175], v[174:175], 0, v[196:197]
	v_lshl_add_u64 v[176:177], v[176:177], 0, v[196:197]
	v_lshl_add_u64 v[178:179], v[178:179], 0, v[196:197]
	v_lshl_add_u64 v[180:181], v[180:181], 0, v[196:197]
	v_lshl_add_u64 v[182:183], v[182:183], 0, v[196:197]
	v_lshl_add_u64 v[184:185], v[184:185], 0, v[196:197]
	v_lshl_add_u64 v[186:187], v[186:187], 0, v[196:197]
	v_lshl_add_u64 v[188:189], v[188:189], 0, v[196:197]
	v_pk_mul_f32 v[126:127], v[126:127], v[150:151] op_sel_hi:[1,0]
	v_pk_mul_f32 v[128:129], v[128:129], v[150:151] op_sel_hi:[1,0]
	v_pk_mul_f32 v[122:123], v[122:123], v[150:151] op_sel_hi:[1,0]
	v_pk_mul_f32 v[124:125], v[124:125], v[150:151] op_sel_hi:[1,0]
	v_pk_mul_f32 v[118:119], v[118:119], v[150:151] op_sel:[0,1]
	v_pk_mul_f32 v[120:121], v[120:121], v[150:151] op_sel:[0,1]
	v_pk_mul_f32 v[114:115], v[114:115], v[150:151] op_sel:[0,1]
	v_pk_mul_f32 v[116:117], v[116:117], v[150:151] op_sel:[0,1]
	v_pk_mul_f32 v[110:111], v[110:111], v[152:153] op_sel_hi:[1,0]
	v_pk_mul_f32 v[112:113], v[112:113], v[152:153] op_sel_hi:[1,0]
	v_pk_mul_f32 v[106:107], v[106:107], v[152:153] op_sel_hi:[1,0]
	v_pk_mul_f32 v[108:109], v[108:109], v[152:153] op_sel_hi:[1,0]
	v_pk_mul_f32 v[102:103], v[102:103], v[152:153] op_sel:[0,1]
	v_pk_mul_f32 v[104:105], v[104:105], v[152:153] op_sel:[0,1]
	v_pk_mul_f32 v[98:99], v[98:99], v[152:153] op_sel:[0,1]
	v_pk_mul_f32 v[100:101], v[100:101], v[152:153] op_sel:[0,1]
	v_pk_mul_f32 v[94:95], v[94:95], v[150:151] op_sel_hi:[1,0]
	v_pk_mul_f32 v[96:97], v[96:97], v[150:151] op_sel_hi:[1,0]
	v_pk_mul_f32 v[90:91], v[90:91], v[150:151] op_sel_hi:[1,0]
	v_pk_mul_f32 v[92:93], v[92:93], v[150:151] op_sel_hi:[1,0]
	v_pk_mul_f32 v[86:87], v[86:87], v[150:151] op_sel:[0,1]
	v_pk_mul_f32 v[88:89], v[88:89], v[150:151] op_sel:[0,1]
	v_pk_mul_f32 v[82:83], v[82:83], v[150:151] op_sel:[0,1]
	v_pk_mul_f32 v[84:85], v[84:85], v[150:151] op_sel:[0,1]
	v_pk_mul_f32 v[78:79], v[78:79], v[152:153] op_sel_hi:[1,0]
	v_pk_mul_f32 v[80:81], v[80:81], v[152:153] op_sel_hi:[1,0]
	v_pk_mul_f32 v[74:75], v[74:75], v[152:153] op_sel_hi:[1,0]
	v_pk_mul_f32 v[76:77], v[76:77], v[152:153] op_sel_hi:[1,0]
; __device__ __forceinline__ unsigned pk2(float lo, float hi) { const f2_t v = {lo, hi}; return __builtin_bit_cast(unsigned, __builtin_convertvector(v, bf2_t)); }
; #define EPI_LOOP for (int ai = 0; ai < 2; ++ai) for (int bj = 0; bj < 2; ++bj) for (int m = 0; m < 4; ++m) for (int n = 0; n < 2; ++n)
;   __device__ __forceinline__ void operator()(const f32x4 (&acc)[2][2][4][2], int pm, int pn, int wr_, int wc_, int fr_, int fq_, bf16_t* shm, int tid) const {
;     const int wr = tid >> 8, wc = (tid >> 6) & 3, fr = tid & 15, fq = (tid >> 4) & 3;
; #pragma unroll
;     EPI_LOOP { EPI_RC
;       const float s = rstd[2 * row + 1];
;       int b, key; if (row < NLAT) { b = row >> 11; key = row & 2047; } else { b = (row - NLAT) >> 8; key = 2048 + ((row - NLAT) & 255); }
;       const int h = col >> 6, d = col & 63;
;       u32x2 w; w.x = pk2(v[0] * s, v[1] * s); w.y = pk2(v[2] * s, v[3] * s);
;       *(u32x2*)(Kn + (((long)(b * 8 + h) * 2304 + key) << 6) + d) = w; }
;   }
	v_pk_mul_f32 v[70:71], v[70:71], v[152:153] op_sel:[0,1]
	v_pk_mul_f32 v[72:73], v[72:73], v[152:153] op_sel:[0,1]
	v_pk_mul_f32 v[66:67], v[66:67], v[152:153] op_sel:[0,1]
	v_pk_mul_f32 v[68:69], v[68:69], v[152:153] op_sel:[0,1]
	v_pk_mul_f32 v[62:63], v[62:63], v[154:155] op_sel_hi:[1,0]
	v_pk_mul_f32 v[64:65], v[64:65], v[154:155] op_sel_hi:[1,0]
	v_pk_mul_f32 v[58:59], v[58:59], v[154:155] op_sel_hi:[1,0]
	v_pk_mul_f32 v[60:61], v[60:61], v[154:155] op_sel_hi:[1,0]
	v_pk_mul_f32 v[54:55], v[54:55], v[154:155] op_sel:[0,1]
	v_pk_mul_f32 v[56:57], v[56:57], v[154:155] op_sel:[0,1]
	v_pk_mul_f32 v[50:51], v[50:51], v[154:155] op_sel:[0,1]
	v_pk_mul_f32 v[52:53], v[52:53], v[154:155] op_sel:[0,1]
	v_pk_mul_f32 v[46:47], v[46:47], v[156:157] op_sel_hi:[1,0]
	v_pk_mul_f32 v[48:49], v[48:49], v[156:157] op_sel_hi:[1,0]
	v_pk_mul_f32 v[42:43], v[42:43], v[156:157] op_sel_hi:[1,0]
	v_pk_mul_f32 v[44:45], v[44:45], v[156:157] op_sel_hi:[1,0]
	v_pk_mul_f32 v[38:39], v[38:39], v[156:157] op_sel:[0,1]
	v_pk_mul_f32 v[40:41], v[40:41], v[156:157] op_sel:[0,1]
	v_pk_mul_f32 v[34:35], v[34:35], v[156:157] op_sel:[0,1]
	v_pk_mul_f32 v[36:37], v[36:37], v[156:157] op_sel:[0,1]
	v_pk_mul_f32 v[30:31], v[30:31], v[154:155] op_sel_hi:[1,0]
	v_pk_mul_f32 v[32:33], v[32:33], v[154:155] op_sel_hi:[1,0]
	v_pk_mul_f32 v[26:27], v[26:27], v[154:155] op_sel_hi:[1,0]
	v_pk_mul_f32 v[28:29], v[28:29], v[154:155] op_sel_hi:[1,0]
	v_pk_mul_f32 v[22:23], v[22:23], v[154:155] op_sel:[0,1]
	v_pk_mul_f32 v[24:25], v[24:25], v[154:155] op_sel:[0,1]
	v_pk_mul_f32 v[18:19], v[18:19], v[154:155] op_sel:[0,1]
	v_pk_mul_f32 v[20:21], v[20:21], v[154:155] op_sel:[0,1]
	v_pk_mul_f32 v[14:15], v[14:15], v[156:157] op_sel_hi:[1,0]
	v_pk_mul_f32 v[16:17], v[16:17], v[156:157] op_sel_hi:[1,0]
	v_pk_mul_f32 v[10:11], v[10:11], v[156:157] op_sel_hi:[1,0]
	v_pk_mul_f32 v[12:13], v[12:13], v[156:157] op_sel_hi:[1,0]
	v_pk_mul_f32 v[6:7], v[6:7], v[156:157] op_sel:[0,1]
	v_pk_mul_f32 v[8:9], v[8:9], v[156:157] op_sel:[0,1]
	v_pk_mul_f32 v[2:3], v[2:3], v[156:157] op_sel:[0,1]
	v_pk_mul_f32 v[4:5], v[4:5], v[156:157] op_sel:[0,1]
	s_nop 0
	v_cvt_pk_bf16_f32 v126, v126, v127
	v_cvt_pk_bf16_f32 v127, v128, v129
	v_cvt_pk_bf16_f32 v128, v122, v123
	v_cvt_pk_bf16_f32 v129, v124, v125
	v_cvt_pk_bf16_f32 v118, v118, v119
	v_cvt_pk_bf16_f32 v119, v120, v121
	v_cvt_pk_bf16_f32 v120, v114, v115
	v_cvt_pk_bf16_f32 v121, v116, v117
	v_cvt_pk_bf16_f32 v110, v110, v111
	v_cvt_pk_bf16_f32 v111, v112, v113
	v_cvt_pk_bf16_f32 v112, v106, v107
	v_cvt_pk_bf16_f32 v113, v108, v109
	v_cvt_pk_bf16_f32 v102, v102, v103
	v_cvt_pk_bf16_f32 v103, v104, v105
	v_cvt_pk_bf16_f32 v104, v98, v99
	v_cvt_pk_bf16_f32 v105, v100, v101
	v_cvt_pk_bf16_f32 v94, v94, v95
	v_cvt_pk_bf16_f32 v95, v96, v97
	v_cvt_pk_bf16_f32 v96, v90, v91
	v_cvt_pk_bf16_f32 v97, v92, v93
	v_cvt_pk_bf16_f32 v86, v86, v87
	v_cvt_pk_bf16_f32 v87, v88, v89
	v_cvt_pk_bf16_f32 v88, v82, v83
	v_cvt_pk_bf16_f32 v89, v84, v85
	v_cvt_pk_bf16_f32 v78, v78, v79
	v_cvt_pk_bf16_f32 v79, v80, v81
	v_cvt_pk_bf16_f32 v80, v74, v75
	v_cvt_pk_bf16_f32 v81, v76, v77
	v_cvt_pk_bf16_f32 v70, v70, v71
	v_cvt_pk_bf16_f32 v71, v72, v73
	v_cvt_pk_bf16_f32 v72, v66, v67
	v_cvt_pk_bf16_f32 v73, v68, v69
	v_cvt_pk_bf16_f32 v62, v62, v63
	v_cvt_pk_bf16_f32 v63, v64, v65
	v_cvt_pk_bf16_f32 v64, v58, v59
	v_cvt_pk_bf16_f32 v65, v60, v61
	v_cvt_pk_bf16_f32 v54, v54, v55
	v_cvt_pk_bf16_f32 v55, v56, v57
	v_cvt_pk_bf16_f32 v56, v50, v51
	v_cvt_pk_bf16_f32 v57, v52, v53
	v_cvt_pk_bf16_f32 v46, v46, v47
	v_cvt_pk_bf16_f32 v47, v48, v49
	v_cvt_pk_bf16_f32 v48, v42, v43
	v_cvt_pk_bf16_f32 v49, v44, v45
	v_cvt_pk_bf16_f32 v38, v38, v39
	v_cvt_pk_bf16_f32 v39, v40, v41
	v_cvt_pk_bf16_f32 v40, v34, v35
	v_cvt_pk_bf16_f32 v41, v36, v37
	v_cvt_pk_bf16_f32 v30, v30, v31
	v_cvt_pk_bf16_f32 v31, v32, v33
	v_cvt_pk_bf16_f32 v32, v26, v27
	v_cvt_pk_bf16_f32 v33, v28, v29
	v_cvt_pk_bf16_f32 v22, v22, v23
	v_cvt_pk_bf16_f32 v23, v24, v25
	v_cvt_pk_bf16_f32 v24, v18, v19
	v_cvt_pk_bf16_f32 v25, v20, v21
	v_cvt_pk_bf16_f32 v14, v14, v15
	v_cvt_pk_bf16_f32 v15, v16, v17
	v_cvt_pk_bf16_f32 v16, v10, v11
	v_cvt_pk_bf16_f32 v17, v12, v13
	v_cvt_pk_bf16_f32 v6, v6, v7
	v_cvt_pk_bf16_f32 v7, v8, v9
	v_cvt_pk_bf16_f32 v8, v2, v3
	v_cvt_pk_bf16_f32 v9, v4, v5
	s_nop 1
	v_permlane16_swap_b32_e32 v126, v128
	v_permlane16_swap_b32_e32 v127, v129
	v_permlane16_swap_b32_e32 v118, v120
	v_permlane16_swap_b32_e32 v119, v121
	v_permlane16_swap_b32_e32 v110, v112
	v_permlane16_swap_b32_e32 v111, v113
	v_permlane16_swap_b32_e32 v102, v104
	v_permlane16_swap_b32_e32 v103, v105
	v_permlane16_swap_b32_e32 v94, v96
	v_permlane16_swap_b32_e32 v95, v97
	v_permlane16_swap_b32_e32 v86, v88
	v_permlane16_swap_b32_e32 v87, v89
	v_permlane16_swap_b32_e32 v78, v80
	v_permlane16_swap_b32_e32 v79, v81
	v_permlane16_swap_b32_e32 v70, v72
	v_permlane16_swap_b32_e32 v71, v73
	v_permlane16_swap_b32_e32 v62, v64
	v_permlane16_swap_b32_e32 v63, v65
	v_permlane16_swap_b32_e32 v54, v56
	v_permlane16_swap_b32_e32 v55, v57
	v_permlane16_swap_b32_e32 v46, v48
	v_permlane16_swap_b32_e32 v47, v49
	v_permlane16_swap_b32_e32 v38, v40
	v_permlane16_swap_b32_e32 v39, v41
	v_permlane16_swap_b32_e32 v30, v32
	v_permlane16_swap_b32_e32 v31, v33
	v_permlane16_swap_b32_e32 v22, v24
	v_permlane16_swap_b32_e32 v23, v25
	v_permlane16_swap_b32_e32 v14, v16
	v_permlane16_swap_b32_e32 v15, v17
	v_permlane16_swap_b32_e32 v6, v8
	v_permlane16_swap_b32_e32 v7, v9
	global_store_dwordx4 v[140:141], v[126:129], off
	global_store_dwordx4 v[160:161], v[118:121], off
	global_store_dwordx4 v[162:163], v[110:113], off
	global_store_dwordx4 v[164:165], v[102:105], off
	global_store_dwordx4 v[174:175], v[94:97], off
	global_store_dwordx4 v[176:177], v[86:89], off
	global_store_dwordx4 v[178:179], v[78:81], off
	global_store_dwordx4 v[180:181], v[70:73], off
	global_store_dwordx4 v[166:167], v[62:65], off
	global_store_dwordx4 v[168:169], v[54:57], off
	global_store_dwordx4 v[170:171], v[46:49], off
	global_store_dwordx4 v[172:173], v[38:41], off
	global_store_dwordx4 v[182:183], v[30:33], off
	global_store_dwordx4 v[184:185], v[22:25], off
	global_store_dwordx4 v[186:187], v[14:17], off
	global_store_dwordx4 v[188:189], v[6:9], off
	s_mov_b32 s13, s12
	s_andn2_b64 vcc, exec, s[8:9]
	s_waitcnt vmcnt(0)
	s_cbranch_vccz .LBB0_702

; __device__ __forceinline__ float bf2f(bf16_t v) { return __uint_as_float(((unsigned)v) << 16); }
; __device__ __forceinline__ float bflo(unsigned w) { return __uint_as_float(w << 16); }
; __device__ __forceinline__ float bfhi(unsigned w) { return __uint_as_float(w & 0xffff0000u); }
; #define otid() otid_impl(w0)
; __device__ void mlaprep_phase(const Params& p, int w0) {
;   const int tid = otid(); const int lane = tid & 63, wv = tid >> 6;
;   for (int r = blockIdx.x * 8 + wv; r < MTOT; r += gridDim.x * 8) {
;     const bf16_t* pr = p.P + (long)r * DIN;
;     const u32x2 cq = *(const u32x2*)(pr + MCQ + lane * 4);
;     const unsigned ck = *(const unsigned*)(pr + MCKV + lane * 2);
;     float sq = bflo(cq.x) * bflo(cq.x) + bfhi(cq.x) * bfhi(cq.x) + bflo(cq.y) * bflo(cq.y) + bfhi(cq.y) * bfhi(cq.y);
;     float sk = bflo(ck) * bflo(ck) + bfhi(ck) * bfhi(ck);
; #pragma unroll
;     for (int o = 32; o > 0; o >>= 1) { sq += __shfl_xor(sq, o); sk += __shfl_xor(sk, o); }
;     if (lane == 0) { p.rstd[2 * r] = rsqrtf(sq * (1.f / 256.f) + EPS); p.rstd[2 * r + 1] = rsqrtf(sk * (1.f / 128.f) + EPS); }
;     const float kv = bf2f(pr[MKR + (lane & 31)]);
.LBB0_926:
	v_readlane_b32 s0, v250, 0
	s_barrier
	s_waitcnt vmcnt(3)
	v_mbcnt_lo_u32_b32 v2, -1, 0
	v_mbcnt_hi_u32_b32 v2, -1, v2
	s_nop 0
	v_add_u32_e32 v0, s0, v2
	v_ashrrev_i32_e32 v0, 6, v0
	v_readlane_b32 s0, v250, 39
	s_nop 1
	v_add_u32_e32 v16, s0, v0
	s_mov_b32 s0, 0x12000
	v_cmp_gt_i32_e32 vcc, s0, v16
	s_and_saveexec_b64 s[0:1], vcc
	s_cbranch_execz .LBB0_937
	v_and_b32_e32 v4, 64, v226
	v_readlane_b32 s8, v253, 7
	v_add_u32_e32 v4, 64, v4
	v_readlane_b32 s9, v253, 8
	s_waitcnt vmcnt(2)
	v_xor_b32_e32 v7, 32, v226
	v_cmp_lt_i32_e64 s[8:9], v7, v4
	v_and_b32_e32 v3, 63, v2
	v_lshlrev_b32_e32 v6, 2, v3
	v_cndmask_b32_e64 v7, v226, v7, s[8:9]
	v_lshlrev_b32_e32 v17, 2, v7
	v_xor_b32_e32 v7, 16, v226
	v_cmp_lt_i32_e64 s[8:9], v7, v4
	v_lshlrev_b32_e32 v8, 1, v3
	v_mov_b32_e32 v9, v1
	v_cndmask_b32_e64 v7, v226, v7, s[8:9]
	v_lshlrev_b32_e32 v18, 2, v7
	v_xor_b32_e32 v7, 8, v226
	v_cmp_lt_i32_e64 s[8:9], v7, v4
	s_waitcnt vmcnt(1)
	v_and_b32_e32 v10, 31, v2
	v_and_b32_e32 v5, 23, v2
	v_cndmask_b32_e64 v7, v226, v7, s[8:9]
	v_lshlrev_b32_e32 v19, 2, v7
	v_xor_b32_e32 v7, 4, v226
	v_cmp_lt_i32_e64 s[8:9], v7, v4
	v_and_b32_e32 v2, 8, v2
	v_readlane_b32 s12, v253, 11
	v_cndmask_b32_e64 v7, v226, v7, s[8:9]
	v_lshlrev_b32_e32 v20, 2, v7
	v_xor_b32_e32 v7, 2, v226
	v_cmp_lt_i32_e64 s[8:9], v7, v4
	v_readlane_b32 s13, v253, 12
	v_readlane_b32 s14, v253, 13
	v_cndmask_b32_e64 v7, v226, v7, s[8:9]
	v_lshlrev_b32_e32 v21, 2, v7
	v_xor_b32_e32 v7, 1, v226
	v_cmp_lt_i32_e64 s[8:9], v7, v4
	v_readlane_b32 s15, v253, 14
	v_readlane_b32 s2, v250, 6
	v_cndmask_b32_e64 v4, v226, v7, s[8:9]
	v_cmp_eq_u32_e32 vcc, 0, v3
	v_cmp_eq_u32_e64 s[4:5], 0, v2
	v_cmp_gt_u32_e64 s[6:7], 32, v3
	v_lshl_add_u64 v[2:3], s[14:15], 0, v[8:9]
	v_lshlrev_b32_e32 v22, 2, v4
	v_lshl_add_u32 v4, v0, 1, s2
	s_mov_b64 s[12:13], 0
	v_lshlrev_b32_e32 v0, 1, v6
	v_lshlrev_b32_e32 v6, 1, v8
	v_lshlrev_b32_e32 v8, 1, v10
	v_lshlrev_b32_e32 v23, 2, v5
	v_readlane_b32 s10, v253, 9
	v_readlane_b32 s11, v253, 10
	v_readlane_b32 s16, v253, 15
	v_readlane_b32 s17, v253, 16
	v_readlane_b32 s18, v253, 17
	v_readlane_b32 s19, v253, 18
	v_readlane_b32 s20, v253, 19
	v_readlane_b32 s21, v253, 20
	v_readlane_b32 s22, v253, 21
	v_readlane_b32 s23, v253, 22
	v_readlane_b32 s24, v252, 28
	v_readlane_b32 s25, v252, 29
	s_movk_i32 s2, 0xf80
	v_mov_b32_e32 v7, v1
	v_mov_b32_e32 v9, v1
	v_mov_b64_e32 v[184:185], s[24:25]
	v_mad_i64_i32 v[184:185], s[8:9], v16, s2, v[184:185]
	v_lshl_add_u64 v[186:187], v[184:185], 0, v[0:1]
	global_load_dwordx2 v[180:181], v[186:187], off offset:3136
	v_lshl_add_u64 v[186:187], v[184:185], 0, v[6:7]
	global_load_dword v182, v[186:187], off offset:3648
	v_lshl_add_u64 v[186:187], v[184:185], 0, v[8:9]
	global_load_ushort v183, v[186:187], off offset:3904
	s_waitcnt vmcnt(0)
	s_branch .LBB0_929

; __device__ __forceinline__ bf16_t f2bf(float f) { return (bf16_t)(pk2(f, 0.f) & 0xffffu); }
; __device__ __forceinline__ float bf2f(bf16_t v) { return __uint_as_float(((unsigned)v) << 16); }
; __device__ __forceinline__ float bflo(unsigned w) { return __uint_as_float(w << 16); }
; __device__ __forceinline__ float bfhi(unsigned w) { return __uint_as_float(w & 0xffff0000u); }
; __device__ void mlaprep_phase(const Params& p, int w0) {
;     ...
;   for (int r = blockIdx.x * 8 + wv; r < MTOT; r += gridDim.x * 8) {
;     const bf16_t* pr = p.P + (long)r * DIN;
;     const u32x2 cq = *(const u32x2*)(pr + MCQ + lane * 4);
;     const unsigned ck = *(const unsigned*)(pr + MCKV + lane * 2);
;     float sq = bflo(cq.x) * bflo(cq.x) + bfhi(cq.x) * bfhi(cq.x) + bflo(cq.y) * bflo(cq.y) + bfhi(cq.y) * bfhi(cq.y);
;     float sk = bflo(ck) * bflo(ck) + bfhi(ck) * bfhi(ck);
; #pragma unroll
;     for (int o = 32; o > 0; o >>= 1) { sq += __shfl_xor(sq, o); sk += __shfl_xor(sk, o); }
;     if (lane == 0) { p.rstd[2 * r] = rsqrtf(sq * (1.f / 256.f) + EPS); p.rstd[2 * r + 1] = rsqrtf(sk * (1.f / 128.f) + EPS); }
;     const float kv = bf2f(pr[MKR + (lane & 31)]);
;     float outv = kv; int b, key;
;     if (r < NLAT) {
;       b = r >> 11; key = r & 2047;
;       const float other = __shfl_xor(kv, 8);
;       const int i = lane & 7, part = (lane >> 4) & 1;
;       const float cs = p.ropetab[key * 32 + part * 16 + i], sn = p.ropetab[key * 32 + part * 16 + 8 + i];
;       outv = (lane & 8) ? (other * sn + kv * cs) : (kv * cs - other * sn);
;     } else { b = (r - NLAT) >> 8; key = 2048 + ((r - NLAT) & 255); }
;     if (lane < 32) p.Kr[((long)b * 2304 + key) * 32 + lane] = f2bf(outv);
.LBB0_929:
	v_readlane_b32 s16, v252, 20
	v_readlane_b32 s24, v252, 28
	v_readlane_b32 s25, v252, 29
	v_readlane_b32 s18, v252, 5
	v_readlane_b32 s19, v252, 6
	v_readlane_b32 s20, v251, 34
	s_movk_i32 s2, 0xf80
	v_mov_b32_e32 v7, v1
	v_mov_b32_e32 v9, v1
	v_mov_b64_e32 v[10:11], s[24:25]
	v_and_b32_e32 v188, 0x7ff, v16
	v_lshl_or_b32 v188, v188, 7, v23
	v_add_u32_e32 v192, s20, v16
	v_min_i32_e32 v192, 0x11fff, v192
	s_waitcnt vmcnt(2)
	v_mov_b64_e32 v[12:13], v[180:181]
	v_mov_b32_e32 v5, v182
	v_mov_b32_e32 v189, v183
	global_load_dword v190, v188, s[18:19] offset:32
	global_load_dword v191, v188, s[18:19]
	v_mad_i64_i32 v[184:185], s[8:9], v192, s2, v[10:11]
	v_lshl_add_u64 v[186:187], v[184:185], 0, v[0:1]
	global_load_dwordx2 v[180:181], v[186:187], off offset:3136
	v_lshl_add_u64 v[186:187], v[184:185], 0, v[6:7]
	global_load_dword v182, v[186:187], off offset:3648
	v_lshl_add_u64 v[186:187], v[184:185], 0, v[8:9]
	global_load_ushort v183, v[186:187], off offset:3904
	s_waitcnt lgkmcnt(0)
	v_readlane_b32 s17, v252, 21
	v_readlane_b32 s18, v252, 22
	v_readlane_b32 s19, v252, 23
	v_readlane_b32 s20, v252, 24
	v_readlane_b32 s21, v252, 25
	v_readlane_b32 s22, v252, 26
	v_readlane_b32 s23, v252, 27
	v_readlane_b32 s26, v252, 30
	v_readlane_b32 s27, v252, 31
	v_readlane_b32 s28, v252, 32
	v_readlane_b32 s29, v252, 33
	v_readlane_b32 s30, v252, 34
	v_readlane_b32 s31, v252, 35
	v_lshlrev_b32_e32 v15, 16, v13
	v_lshlrev_b32_e32 v14, 16, v12
	v_and_b32_e32 v7, 0xffff0000, v12
	v_pk_mul_f32 v[14:15], v[14:15], v[14:15]
	s_nop 0
	v_fma_f32 v7, v7, v7, v14
	v_add_f32_e32 v12, v15, v7
	v_lshlrev_b32_e32 v15, 16, v5
	v_and_b32_e32 v5, 0xffff0000, v5
	v_and_b32_e32 v14, 0xffff0000, v13
	v_mul_f32_e32 v13, v5, v5
	v_pk_fma_f32 v[12:13], v[14:15], v[14:15], v[12:13]
	ds_bpermute_b32 v14, v17, v12
	ds_bpermute_b32 v15, v17, v13
	s_waitcnt lgkmcnt(0)
	v_pk_add_f32 v[12:13], v[12:13], v[14:15]
	ds_bpermute_b32 v14, v18, v12
	ds_bpermute_b32 v15, v18, v13
	s_waitcnt lgkmcnt(0)
	v_pk_add_f32 v[12:13], v[12:13], v[14:15]
	ds_bpermute_b32 v14, v19, v12
	ds_bpermute_b32 v15, v19, v13
	s_waitcnt lgkmcnt(0)
	v_pk_add_f32 v[12:13], v[12:13], v[14:15]
	ds_bpermute_b32 v14, v20, v12
	ds_bpermute_b32 v15, v20, v13
	s_waitcnt lgkmcnt(0)
	v_pk_add_f32 v[12:13], v[12:13], v[14:15]
	ds_bpermute_b32 v14, v21, v12
	ds_bpermute_b32 v15, v21, v13
	s_waitcnt lgkmcnt(0)
	v_pk_add_f32 v[12:13], v[12:13], v[14:15]
	ds_bpermute_b32 v14, v22, v12
	ds_bpermute_b32 v15, v22, v13
	s_and_saveexec_b64 s[14:15], vcc
	s_cbranch_execz .LBB0_931
	s_mov_b32 s8, 0x3b800000
	v_readlane_b32 s16, v253, 7
	s_waitcnt lgkmcnt(0)
	v_pk_add_f32 v[12:13], v[12:13], v[14:15]
	s_brev_b32 s9, 60
	v_mov_b32_e32 v14, 0x358637bd
	v_ashrrev_i32_e32 v5, 31, v4
	v_readlane_b32 s28, v253, 19
	v_readlane_b32 s29, v253, 20
	v_pk_fma_f32 v[12:13], v[12:13], s[8:9], v[14:15] op_sel_hi:[1,1,0]
	s_mov_b32 s2, 0x800000
	v_lshl_add_u64 v[24:25], v[4:5], 2, s[28:29]
	v_mul_f32_e32 v5, 0x4b800000, v12
	v_cmp_gt_f32_e64 s[10:11], s2, v12
	v_cmp_gt_f32_e64 s[8:9], s2, v13
	s_mov_b32 s2, 0x45800000
	v_cndmask_b32_e64 v5, v12, v5, s[10:11]
	v_rsq_f32_e32 v12, v5
	v_mul_f32_e32 v5, 0x4b800000, v13
	v_cndmask_b32_e64 v5, v13, v5, s[8:9]
	v_rsq_f32_e32 v13, v5
	v_readlane_b32 s17, v253, 8
	v_readlane_b32 s18, v253, 9
	v_readlane_b32 s19, v253, 10
	v_pk_mul_f32 v[14:15], v[12:13], s[2:3] op_sel_hi:[1,0]
	v_readlane_b32 s20, v253, 11
	v_cndmask_b32_e64 v13, v13, v15, s[8:9]
	v_cndmask_b32_e64 v12, v12, v14, s[10:11]
	v_readlane_b32 s21, v253, 12
	v_readlane_b32 s22, v253, 13
	v_readlane_b32 s23, v253, 14
	v_readlane_b32 s24, v253, 15
	v_readlane_b32 s25, v253, 16
	v_readlane_b32 s26, v253, 17
	v_readlane_b32 s27, v253, 18
	v_readlane_b32 s30, v253, 21
	v_readlane_b32 s31, v253, 22
	global_store_dwordx2 v[24:25], v[12:13], off
.LBB0_931:
	s_or_b64 exec, exec, s[14:15]
	v_mov_b32_e32 v9, v1
	v_mov_b32_e32 v7, v189
	s_mov_b32 s2, 0xffff
	v_cmp_lt_i32_e64 s[8:9], s2, v16
	s_and_saveexec_b64 s[10:11], s[8:9]
	s_xor_b64 s[8:9], exec, s[10:11]
	s_cbranch_execz .LBB0_934
	v_add_u32_e32 v5, 0xffff0000, v16
	s_movk_i32 s2, 0x800
	v_lshrrev_b32_e32 v5, 8, v5
	v_or_b32_sdwa v10, v16, s2 dst_sel:DWORD dst_unused:UNUSED_PAD src0_sel:BYTE_0 src1_sel:DWORD
	s_or_saveexec_b64 s[8:9], s[8:9]
	v_lshlrev_b32_e32 v7, 16, v7
	s_xor_b64 exec, exec, s[8:9]
	s_cbranch_execnz .LBB0_935

; __device__ __forceinline__ bf16_t f2bf(float f) { return (bf16_t)(pk2(f, 0.f) & 0xffffu); }
; __device__ __forceinline__ float bf2f(bf16_t v) { return __uint_as_float(((unsigned)v) << 16); }
; __device__ void mlaprep_phase(const Params& p, int w0) {
;     ...
;     const float kv = bf2f(pr[MKR + (lane & 31)]);
;     float outv = kv; int b, key;
;     if (r < NLAT) {
;       b = r >> 11; key = r & 2047;
;       const float other = __shfl_xor(kv, 8);
;       const int i = lane & 7, part = (lane >> 4) & 1;
;       const float cs = p.ropetab[key * 32 + part * 16 + i], sn = p.ropetab[key * 32 + part * 16 + 8 + i];
;       outv = (lane & 8) ? (other * sn + kv * cs) : (kv * cs - other * sn);
;     } else { b = (r - NLAT) >> 8; key = 2048 + ((r - NLAT) & 255); }
;     if (lane < 32) p.Kr[((long)b * 2304 + key) * 32 + lane] = f2bf(outv);
.LBB0_934:
	s_or_saveexec_b64 s[8:9], s[8:9]
	v_lshlrev_b32_e32 v7, 16, v7
	s_xor_b64 exec, exec, s[8:9]
	s_cbranch_execz .LBB0_933
.LBB0_935:
	v_and_b32_e32 v10, 0x7ff, v16
	v_readlane_b32 s16, v252, 3
	v_lshl_or_b32 v5, v10, 7, v23
	v_readlane_b32 s18, v252, 5
	v_readlane_b32 s19, v252, 6
	ds_bpermute_b32 v12, v19, v7
	v_ashrrev_i32_e32 v5, 11, v16
	v_readlane_b32 s17, v252, 4
	v_readlane_b32 s20, v252, 7
	v_readlane_b32 s21, v252, 8
	v_readlane_b32 s22, v252, 9
	v_readlane_b32 s23, v252, 10
	v_readlane_b32 s24, v252, 11
	v_readlane_b32 s25, v252, 12
	v_readlane_b32 s26, v252, 13
	v_readlane_b32 s27, v252, 14
	v_readlane_b32 s28, v252, 15
	v_readlane_b32 s29, v252, 16
	v_readlane_b32 s30, v252, 17
	v_readlane_b32 s31, v252, 18
	s_waitcnt vmcnt(4) lgkmcnt(0)
	v_mul_f32_e32 v9, v190, v12
	v_cndmask_b32_e64 v9, v9, -v9, s[4:5]
	v_fmac_f32_e32 v9, v191, v7
	v_mov_b32_e32 v7, v9
	s_or_b64 exec, exec, s[8:9]
	s_and_saveexec_b64 s[8:9], s[6:7]
	s_cbranch_execz .LBB0_928

; __device__ __forceinline__ unsigned pk2(float lo, float hi) { const f2_t v = {lo, hi}; return __builtin_bit_cast(unsigned, __builtin_convertvector(v, bf2_t)); }
; #define EPI_LOOP for (int ai = 0; ai < 2; ++ai) for (int bj = 0; bj < 2; ++bj) for (int m = 0; m < 4; ++m) for (int n = 0; n < 2; ++n)
;   __device__ __forceinline__ void operator()(const f32x4 (&acc)[2][2][4][2], int pm, int pn, int wr, int wc, int fr, int fq, bf16_t* shm, int tid) const {
; #pragma unroll
;     EPI_LOOP { EPI_RC
;       if (col < DIN) { u32x2 w; w.x = pk2(v[0], v[1]); w.y = pk2(v[2], v[3]); *(u32x2*)(P + (long)row * DIN + col) = w; } }
;   }
.LBB0_1060:
	s_nop 15
	s_nop 15
	v_mbcnt_lo_u32_b32 v0, -1, 0
	v_mbcnt_hi_u32_b32 v0, -1, v0
	v_readlane_b32 s40, v252, 20
	v_add_u32_e32 v0, s0, v146
	s_movk_i32 s0, 0xf80
	v_or_b32_e32 v130, s12, v145
	v_mad_i64_i32 v[132:133], s[0:1], v0, s0, 0
	v_readlane_b32 s48, v252, 28
	v_readlane_b32 s49, v252, 29
	v_cmp_gt_i32_e32 vcc, s59, v130
	v_ashrrev_i32_e32 v131, 31, v130
	v_lshl_add_u64 v[132:133], s[48:49], 0, v[132:133]
	v_and_b32_e32 v192, 4, v145
	v_mul_u32_u24_e32 v193, 3, v192
	v_add_u32_e32 v193, v130, v193
	v_mul_u32_u24_e32 v192, 6, v192
	v_add_u32_e32 v194, 0x80, v193
	v_cmp_gt_i32_e64 s[44:45], s59, v193
	v_cmp_gt_i32_e64 s[46:47], s59, v194
	v_lshl_add_u64 v[176:177], v[130:131], 1, v[132:133]
	v_mov_b32_e32 v193, v1
	v_mov_b32_e32 v194, v192
	v_mov_b32_e32 v195, v1
	v_lshl_add_u64 v[176:177], v[176:177], 0, v[194:195]
	s_mov_b32 s49, 0
	s_mov_b32 s48, 0xf800
	v_lshl_add_u64 v[178:179], v[176:177], 0, s[48:49]
	s_mov_b32 s48, 0x1f000
	v_lshl_add_u64 v[180:181], v[176:177], 0, s[48:49]
	s_mov_b32 s48, 0x2e800
	v_lshl_add_u64 v[182:183], v[176:177], 0, s[48:49]
	s_mov_b32 s48, 0x7c000
	v_lshl_add_u64 v[184:185], v[176:177], 0, s[48:49]
	s_mov_b32 s48, 0x8b800
	v_lshl_add_u64 v[186:187], v[176:177], 0, s[48:49]
	s_mov_b32 s48, 0x9b000
	v_lshl_add_u64 v[188:189], v[176:177], 0, s[48:49]
	s_mov_b32 s48, 0xaa800
	v_lshl_add_u64 v[190:191], v[176:177], 0, s[48:49]
	v_cvt_pk_bf16_f32 v126, v126, v127
	v_cvt_pk_bf16_f32 v127, v128, v129
	v_cvt_pk_bf16_f32 v128, v122, v123
	v_cvt_pk_bf16_f32 v129, v124, v125
	v_cvt_pk_bf16_f32 v118, v118, v119
	v_cvt_pk_bf16_f32 v119, v120, v121
	v_cvt_pk_bf16_f32 v120, v114, v115
	v_cvt_pk_bf16_f32 v121, v116, v117
	v_cvt_pk_bf16_f32 v110, v110, v111
	v_cvt_pk_bf16_f32 v111, v112, v113
	v_cvt_pk_bf16_f32 v112, v106, v107
	v_cvt_pk_bf16_f32 v113, v108, v109
	v_cvt_pk_bf16_f32 v102, v102, v103
	v_cvt_pk_bf16_f32 v103, v104, v105
	v_cvt_pk_bf16_f32 v104, v98, v99
	v_cvt_pk_bf16_f32 v105, v100, v101
	v_cvt_pk_bf16_f32 v94, v94, v95
	v_cvt_pk_bf16_f32 v95, v96, v97
	v_cvt_pk_bf16_f32 v96, v90, v91
	v_cvt_pk_bf16_f32 v97, v92, v93
	v_cvt_pk_bf16_f32 v86, v86, v87
	v_cvt_pk_bf16_f32 v87, v88, v89
	v_cvt_pk_bf16_f32 v88, v82, v83
	v_cvt_pk_bf16_f32 v89, v84, v85
	v_cvt_pk_bf16_f32 v78, v78, v79
	v_cvt_pk_bf16_f32 v79, v80, v81
	v_cvt_pk_bf16_f32 v80, v74, v75
	v_cvt_pk_bf16_f32 v81, v76, v77
	v_cvt_pk_bf16_f32 v70, v70, v71
	v_cvt_pk_bf16_f32 v71, v72, v73
	v_cvt_pk_bf16_f32 v72, v66, v67
	v_cvt_pk_bf16_f32 v73, v68, v69
	v_cvt_pk_bf16_f32 v62, v62, v63
	v_cvt_pk_bf16_f32 v63, v64, v65
	v_cvt_pk_bf16_f32 v64, v58, v59
	v_cvt_pk_bf16_f32 v65, v60, v61
	v_cvt_pk_bf16_f32 v54, v54, v55
	v_cvt_pk_bf16_f32 v55, v56, v57
	v_cvt_pk_bf16_f32 v56, v50, v51
	v_cvt_pk_bf16_f32 v57, v52, v53
	v_cvt_pk_bf16_f32 v46, v46, v47
	v_cvt_pk_bf16_f32 v47, v48, v49
	v_cvt_pk_bf16_f32 v48, v42, v43
	v_cvt_pk_bf16_f32 v49, v44, v45
	v_cvt_pk_bf16_f32 v38, v38, v39
	v_cvt_pk_bf16_f32 v39, v40, v41
	v_cvt_pk_bf16_f32 v40, v34, v35
	v_cvt_pk_bf16_f32 v41, v36, v37
	v_cvt_pk_bf16_f32 v30, v30, v31
	v_cvt_pk_bf16_f32 v31, v32, v33
	v_cvt_pk_bf16_f32 v32, v26, v27
	v_cvt_pk_bf16_f32 v33, v28, v29
	v_cvt_pk_bf16_f32 v22, v22, v23
	v_cvt_pk_bf16_f32 v23, v24, v25
	v_cvt_pk_bf16_f32 v24, v18, v19
	v_cvt_pk_bf16_f32 v25, v20, v21
	v_cvt_pk_bf16_f32 v14, v14, v15
	v_cvt_pk_bf16_f32 v15, v16, v17
	v_cvt_pk_bf16_f32 v16, v10, v11
	v_cvt_pk_bf16_f32 v17, v12, v13
	v_cvt_pk_bf16_f32 v6, v6, v7
	v_cvt_pk_bf16_f32 v7, v8, v9
	v_cvt_pk_bf16_f32 v8, v2, v3
	v_cvt_pk_bf16_f32 v9, v4, v5
	s_nop 1
	v_permlane16_swap_b32_e32 v126, v128
	v_permlane16_swap_b32_e32 v127, v129
	v_permlane16_swap_b32_e32 v118, v120
	v_permlane16_swap_b32_e32 v119, v121
	v_permlane16_swap_b32_e32 v110, v112
	v_permlane16_swap_b32_e32 v111, v113
	v_permlane16_swap_b32_e32 v102, v104
	v_permlane16_swap_b32_e32 v103, v105
	v_permlane16_swap_b32_e32 v94, v96
	v_permlane16_swap_b32_e32 v95, v97
	v_permlane16_swap_b32_e32 v86, v88
	v_permlane16_swap_b32_e32 v87, v89
	v_permlane16_swap_b32_e32 v78, v80
	v_permlane16_swap_b32_e32 v79, v81
	v_permlane16_swap_b32_e32 v70, v72
	v_permlane16_swap_b32_e32 v71, v73
	v_permlane16_swap_b32_e32 v62, v64
	v_permlane16_swap_b32_e32 v63, v65
	v_permlane16_swap_b32_e32 v54, v56
	v_permlane16_swap_b32_e32 v55, v57
	v_permlane16_swap_b32_e32 v46, v48
	v_permlane16_swap_b32_e32 v47, v49
	v_permlane16_swap_b32_e32 v38, v40
	v_permlane16_swap_b32_e32 v39, v41
	v_permlane16_swap_b32_e32 v30, v32
	v_permlane16_swap_b32_e32 v31, v33
	v_permlane16_swap_b32_e32 v22, v24
	v_permlane16_swap_b32_e32 v23, v25
	v_permlane16_swap_b32_e32 v14, v16
	v_permlane16_swap_b32_e32 v15, v17
	v_permlane16_swap_b32_e32 v6, v8
	v_permlane16_swap_b32_e32 v7, v9
	v_or_b32_e32 v192, 16, v130
	v_cmp_gt_i32_e64 s[10:11], s59, v192
	v_or_b32_e32 v192, 0x80, v130
	v_cmp_gt_i32_e64 s[12:13], s59, v192
	v_or_b32_e32 v192, 0x90, v130
	v_cmp_gt_i32_e64 s[14:15], s59, v192
	v_readlane_b32 s40, v252, 20
	v_readlane_b32 s41, v252, 21
	v_readlane_b32 s42, v252, 22
	v_readlane_b32 s43, v252, 23
	s_and_saveexec_b64 s[0:1], s[44:45]
	global_store_dwordx4 v[176:177], v[126:129], off
	global_store_dwordx4 v[178:179], v[118:121], off
	global_store_dwordx4 v[180:181], v[110:113], off
	global_store_dwordx4 v[182:183], v[102:105], off
	global_store_dwordx4 v[184:185], v[62:65], off
	global_store_dwordx4 v[186:187], v[54:57], off
	global_store_dwordx4 v[188:189], v[46:49], off
	global_store_dwordx4 v[190:191], v[38:41], off
	s_or_b64 exec, exec, s[0:1]
	s_and_saveexec_b64 s[0:1], s[46:47]
	global_store_dwordx4 v[176:177], v[94:97], off offset:256
	global_store_dwordx4 v[178:179], v[86:89], off offset:256
	global_store_dwordx4 v[180:181], v[78:81], off offset:256
	global_store_dwordx4 v[182:183], v[70:73], off offset:256
	global_store_dwordx4 v[184:185], v[30:33], off offset:256
	global_store_dwordx4 v[186:187], v[22:25], off offset:256
	global_store_dwordx4 v[188:189], v[14:17], off offset:256
	global_store_dwordx4 v[190:191], v[6:9], off offset:256
	s_branch .LBB0_1049
